# attention KV loop: per-tile barrier hoisted above the register-only softmax tail (fma+exp)
# baseline (speedup 1.0000x reference)
; __device__ __forceinline__ void partialSM(f32x16& p0, f32x16& p1, float& m_reg, float& mn, float& alpha) {
;     ...
;     const float mnL = -mn * C2;
;     for (int r = 0; r < 16; ++r) p0[r] = fmaf(p0[r], C2, mnL); for (int r = 0; r < 16; ++r) p1[r] = fmaf(p1[r], C2, mnL);
;     for (int r = 0; r < 16; ++r) p0[r] = __builtin_amdgcn_exp2f(p0[r]);
; }
; __device__ __forceinline__ void finishSM(f32x16& p0, f32x16& p1, float alpha, float& l_reg, bf16x8& pa0, bf16x8& pa1, bf16x8& pa2, bf16x8& pa3) {
;     for (int r = 0; r < 16; ++r) p1[r] = __builtin_amdgcn_exp2f(p1[r]);
;     float ps;
;     {
;       float s0 = p0[0] + p1[0], s1 = p0[1] + p1[1], s2 = p0[2] + p1[2], s3 = p0[3] + p1[3];
; #pragma unroll
;       for (int r = 4; r < 16; r += 4) { s0 += p0[r]; s1 += p0[r + 1]; s2 += p0[r + 2]; s3 += p0[r + 3]; s0 += p1[r]; s1 += p1[r + 1]; s2 += p1[r + 2]; s3 += p1[r + 3]; }
;       ps = (s0 + s1) + (s2 + s3); }
;     { auto rr = __builtin_amdgcn_permlane32_swap(__float_as_uint(ps), __float_as_uint(ps), false, false);
;       ps = __uint_as_float(rr[0]) + __uint_as_float(rr[1]); }
;     l_reg = l_reg * alpha + ps;
;     ...
;     PK4(p0, 0, pa0); PK4(p0, 8, pa1); PK4(p1, 0, pa2); PK4(p1, 8, pa3);
;     ...
; }
; template <int KB, bool SK>
; __device__ __forceinline__ void qkt(f32x16& p0, f32x16& p1, const char* K_lds, int r32, int hi, const bf16x8* qr, bool act) {
;     if (SK && !act) { const float NEG = -__builtin_inff();
; #pragma unroll
;         for (int r = 0; r < 16; ++r) { p0[r] = NEG; p1[r] = NEG; } return; }
;     p0 = f32x16{}; p1 = f32x16{};
;     const char* kb[4];
; #pragma unroll
;     for (int dd = 0; dd < 4; ++dd) kb[dd] = K_lds + KB * SHM_K + KSWZ(r32, (dd * 16 + hi * 8) * 2);
; #pragma unroll
;     for (int d0 = 0; d0 < 8; ++d0) { const char* a = kb[d0 & 3] + (d0 >> 2) * 128;
;         bf16x8 b0 = *reinterpret_cast<const bf16x8*>(a);
;         bf16x8 b1 = *reinterpret_cast<const bf16x8*>(a + 32 * 256);
;         p0 = __builtin_amdgcn_mfma_f32_32x32x16_bf16(b0, qr[d0], p0, 0, 0, 0);
;         p1 = __builtin_amdgcn_mfma_f32_32x32x16_bf16(b1, qr[d0], p1, 0, 0, 0); }
.LBB0_389:
	s_waitcnt lgkmcnt(0)
	s_barrier
	v_cndmask_b32_e64 v235, v2, v188, s[6:7]
	v_mul_f32_e32 v2, 0xbe0293ee, v235
	v_fmamk_f32 v84, v84, 0x3e0293ee, v2
	v_fmamk_f32 v85, v85, 0x3e0293ee, v2
	v_fmamk_f32 v86, v86, 0x3e0293ee, v2
	v_fmamk_f32 v87, v87, 0x3e0293ee, v2
	v_fmamk_f32 v88, v88, 0x3e0293ee, v2
	v_fmamk_f32 v89, v89, 0x3e0293ee, v2
	v_fmamk_f32 v90, v90, 0x3e0293ee, v2
	v_fmamk_f32 v91, v91, 0x3e0293ee, v2
	v_fmamk_f32 v92, v92, 0x3e0293ee, v2
	v_fmamk_f32 v93, v93, 0x3e0293ee, v2
	v_fmamk_f32 v94, v94, 0x3e0293ee, v2
	v_fmamk_f32 v95, v95, 0x3e0293ee, v2
	v_fmamk_f32 v96, v96, 0x3e0293ee, v2
	v_fmamk_f32 v97, v97, 0x3e0293ee, v2
	v_fmamk_f32 v98, v98, 0x3e0293ee, v2
	v_fmamk_f32 v99, v99, 0x3e0293ee, v2
	v_fmamk_f32 v180, v68, 0x3e0293ee, v2
	v_fmamk_f32 v181, v69, 0x3e0293ee, v2
	v_fmamk_f32 v182, v70, 0x3e0293ee, v2
	v_fmamk_f32 v183, v71, 0x3e0293ee, v2
	v_fmamk_f32 v184, v72, 0x3e0293ee, v2
	v_fmamk_f32 v185, v73, 0x3e0293ee, v2
	v_fmamk_f32 v186, v74, 0x3e0293ee, v2
	v_fmamk_f32 v187, v75, 0x3e0293ee, v2
	v_fmamk_f32 v188, v76, 0x3e0293ee, v2
	v_fmamk_f32 v189, v77, 0x3e0293ee, v2
	v_fmamk_f32 v190, v78, 0x3e0293ee, v2
	v_fmamk_f32 v191, v79, 0x3e0293ee, v2
	v_fmamk_f32 v192, v80, 0x3e0293ee, v2
	v_fmamk_f32 v193, v81, 0x3e0293ee, v2
	v_fmamk_f32 v194, v82, 0x3e0293ee, v2
	v_fmac_f32_e32 v2, 0x3e0293ee, v83
	v_exp_f32_e32 v68, v84
	v_exp_f32_e32 v69, v85
	v_exp_f32_e32 v70, v86
	v_exp_f32_e32 v71, v87
	v_exp_f32_e32 v72, v88
	v_exp_f32_e32 v73, v89
	v_exp_f32_e32 v74, v90
	v_exp_f32_e32 v75, v91
	v_exp_f32_e32 v76, v92
	v_exp_f32_e32 v77, v93
	v_exp_f32_e32 v78, v94
	v_exp_f32_e32 v79, v95
	v_exp_f32_e32 v80, v96
	v_exp_f32_e32 v81, v97
	v_exp_f32_e32 v82, v98
	v_exp_f32_e32 v83, v99
	ds_write_b128 v223, v[164:167]
	ds_write_b128 v224, v[168:171]
	ds_read_b128 v[84:87], v225 offset:32768
	ds_read_b128 v[88:91], v225 offset:40960
	v_exp_f32_e32 v92, v188
	v_exp_f32_e32 v93, v189
	v_exp_f32_e32 v94, v190
	s_waitcnt lgkmcnt(1)
	v_mfma_f32_32x32x16_bf16 v[116:131], v[84:87], v[160:163], 0
	v_exp_f32_e32 v95, v191
	v_exp_f32_e32 v99, v2
	v_exp_f32_e32 v96, v192
	v_exp_f32_e32 v97, v193
	v_exp_f32_e32 v98, v194
	s_waitcnt lgkmcnt(0)
	v_mfma_f32_32x32x16_bf16 v[100:115], v[88:91], v[160:163], 0
	ds_read_b128 v[84:87], v226 offset:32768
	ds_read_b128 v[88:91], v226 offset:40960
	s_waitcnt lgkmcnt(1)
	v_mfma_f32_32x32x16_bf16 v[116:131], v[84:87], v[156:159], v[116:131]
	s_waitcnt lgkmcnt(0)
	v_mfma_f32_32x32x16_bf16 v[100:115], v[88:91], v[156:159], v[100:115]
	ds_read_b128 v[84:87], v227 offset:32768
	ds_read_b128 v[88:91], v227 offset:40960
	s_waitcnt lgkmcnt(1)
	v_mfma_f32_32x32x16_bf16 v[116:131], v[84:87], v[152:155], v[116:131]
	s_waitcnt lgkmcnt(0)
	v_mfma_f32_32x32x16_bf16 v[100:115], v[88:91], v[152:155], v[100:115]
	ds_read_b128 v[84:87], v228 offset:32768
	ds_read_b128 v[88:91], v228 offset:40960
	s_waitcnt lgkmcnt(1)
	v_mfma_f32_32x32x16_bf16 v[116:131], v[84:87], v[136:139], v[116:131]
	s_waitcnt lgkmcnt(0)
	v_mfma_f32_32x32x16_bf16 v[100:115], v[88:91], v[136:139], v[100:115]
	ds_read_b128 v[84:87], v225 offset:32896
	ds_read_b128 v[88:91], v225 offset:41088
	s_waitcnt lgkmcnt(1)
	v_mfma_f32_32x32x16_bf16 v[116:131], v[84:87], v[140:143], v[116:131]
	s_waitcnt lgkmcnt(0)
	v_mfma_f32_32x32x16_bf16 v[100:115], v[88:91], v[140:143], v[100:115]
	ds_read_b128 v[84:87], v226 offset:32896
	ds_read_b128 v[88:91], v226 offset:41088
	s_waitcnt lgkmcnt(1)
	v_mfma_f32_32x32x16_bf16 v[116:131], v[84:87], v[144:147], v[116:131]
	s_waitcnt lgkmcnt(0)
	v_mfma_f32_32x32x16_bf16 v[100:115], v[88:91], v[144:147], v[100:115]
	ds_read_b128 v[84:87], v227 offset:32896
	ds_read_b128 v[88:91], v227 offset:41088
	s_waitcnt lgkmcnt(1)
	v_mfma_f32_32x32x16_bf16 v[116:131], v[84:87], v[148:151], v[116:131]
	s_waitcnt lgkmcnt(0)
	v_mfma_f32_32x32x16_bf16 v[100:115], v[88:91], v[148:151], v[100:115]
	ds_read_b128 v[84:87], v228 offset:32896
	ds_read_b128 v[88:91], v228 offset:41088
	s_waitcnt lgkmcnt(1)
	v_mfma_f32_32x32x16_bf16 v[116:131], v[84:87], v[132:135], v[116:131]
	v_exp_f32_e32 v84, v180
	v_exp_f32_e32 v85, v181
	v_exp_f32_e32 v86, v182
	v_exp_f32_e32 v87, v183
	v_add_f32_e32 v2, v68, v84
	v_add_f32_e32 v180, v69, v85
	v_add_f32_e32 v181, v70, v86
	s_waitcnt lgkmcnt(0)
	v_mfma_f32_32x32x16_bf16 v[100:115], v[88:91], v[132:135], v[100:115]
	v_exp_f32_e32 v88, v184
	v_exp_f32_e32 v89, v185
	v_exp_f32_e32 v90, v186
	v_exp_f32_e32 v91, v187
	v_add_f32_e32 v182, v71, v87
	v_add_f32_e32 v2, v72, v2
	v_add_f32_e32 v180, v73, v180
	v_add_f32_e32 v181, v74, v181
	v_add_f32_e32 v182, v75, v182
	v_add_f32_e32 v2, v88, v2
	v_add_f32_e32 v180, v89, v180
	v_add_f32_e32 v181, v90, v181
	v_add_f32_e32 v182, v91, v182
	v_add_f32_e32 v2, v76, v2
	v_add_f32_e32 v180, v77, v180
	v_add_f32_e32 v181, v78, v181
	v_add_f32_e32 v182, v79, v182
	v_add_f32_e32 v2, v92, v2
	v_add_f32_e32 v180, v93, v180
	v_add_f32_e32 v181, v94, v181
	v_add_f32_e32 v182, v95, v182
	v_add_f32_e32 v2, v80, v2
	v_add_f32_e32 v180, v81, v180
	v_add_f32_e32 v181, v82, v181
	v_add_f32_e32 v182, v83, v182
	v_add_f32_e32 v2, v96, v2
	v_add_f32_e32 v180, v97, v180
	v_add_f32_e32 v181, v98, v181
	v_add_f32_e32 v182, v99, v182
	v_add_f32_e32 v2, v180, v2
	v_add_f32_e32 v180, v182, v181
	v_add_f32_e32 v237, v180, v2
	v_mov_b32_e32 v238, v237
	v_cvt_pk_bf16_f32 v180, v68, v69
	v_cvt_pk_bf16_f32 v181, v70, v71
	v_cvt_pk_bf16_f32 v182, v72, v73
	v_cvt_pk_bf16_f32 v183, v74, v75
	v_cvt_pk_bf16_f32 v184, v76, v77
	v_cvt_pk_bf16_f32 v185, v78, v79
	v_cvt_pk_bf16_f32 v186, v80, v81
	v_cvt_pk_bf16_f32 v187, v82, v83
	v_cvt_pk_bf16_f32 v188, v84, v85
	v_cvt_pk_bf16_f32 v189, v86, v87
	v_cvt_pk_bf16_f32 v190, v88, v89
	v_cvt_pk_bf16_f32 v191, v90, v91
	v_cvt_pk_bf16_f32 v192, v92, v93
	v_cvt_pk_bf16_f32 v193, v94, v95
	v_cvt_pk_bf16_f32 v194, v96, v97
	v_cvt_pk_bf16_f32 v195, v98, v99
	s_nop 1
	v_permlane32_swap_b32_e32 v237, v238
	v_permlane32_swap_b32_e32 v180, v182
	v_permlane32_swap_b32_e32 v181, v183
	v_permlane32_swap_b32_e32 v184, v186
	v_permlane32_swap_b32_e32 v185, v187
	v_permlane32_swap_b32_e32 v188, v190
	v_permlane32_swap_b32_e32 v189, v191
	v_permlane32_swap_b32_e32 v192, v194
	v_permlane32_swap_b32_e32 v193, v195
	s_add_i32 s6, s73, 1
	s_cmp_lt_u32 s6, s72
	s_cselect_b64 s[52:53], -1, 0
	s_cmp_ge_u32 s6, s72
	s_cbranch_scc1 .LBB0_391
	v_add_u32_e32 v2, 0x41, v236
	v_lshlrev_b64 v[172:173], 12, v[2:3]
	v_add_u32_e32 v2, 0x61, v236
	v_lshlrev_b64 v[174:175], 12, v[2:3]
	v_lshl_add_u64 v[164:165], v[216:217], 0, v[172:173]
	v_lshl_add_u64 v[168:169], v[216:217], 0, v[174:175]
	v_lshl_add_u64 v[172:173], v[218:219], 0, v[172:173]
	v_lshl_add_u64 v[176:177], v[218:219], 0, v[174:175]
	global_load_dwordx4 v[164:167], v[164:165], off
	s_nop 0
	global_load_dwordx4 v[168:171], v[168:169], off
	s_nop 0
	global_load_dwordx4 v[172:175], v[172:173], off
	s_nop 0
	global_load_dwordx4 v[176:179], v[176:177], off

; __device__ __forceinline__ void partialSM(f32x16& p0, f32x16& p1, float& m_reg, float& mn, float& alpha) {
;     ...
;     constexpr float C2 = 1.4426950408889634f * SCALE;
;     if (__builtin_expect(__all((pmax - m_reg) * SCALE <= THR), 1)) { mn = m_reg; alpha = 1.f; }
;     else { mn = fmaxf(m_reg, pmax); alpha = __builtin_amdgcn_exp2f((m_reg - mn) * C2); m_reg = mn; }
;     const float mnL = -mn * C2;
;     for (int r = 0; r < 16; ++r) p0[r] = fmaf(p0[r], C2, mnL); for (int r = 0; r < 16; ++r) p1[r] = fmaf(p1[r], C2, mnL);
;     for (int r = 0; r < 16; ++r) p0[r] = __builtin_amdgcn_exp2f(p0[r]);
; }
; __device__ __forceinline__ void finishSM(f32x16& p0, f32x16& p1, float alpha, float& l_reg, bf16x8& pa0, bf16x8& pa1, bf16x8& pa2, bf16x8& pa3) {
;     for (int r = 0; r < 16; ++r) p1[r] = __builtin_amdgcn_exp2f(p1[r]);
;     float ps;
;     {
;       float s0 = p0[0] + p1[0], s1 = p0[1] + p1[1], s2 = p0[2] + p1[2], s3 = p0[3] + p1[3];
; #pragma unroll
;       for (int r = 4; r < 16; r += 4) { s0 += p0[r]; s1 += p0[r + 1]; s2 += p0[r + 2]; s3 += p0[r + 3]; s0 += p1[r]; s1 += p1[r + 1]; s2 += p1[r + 2]; s3 += p1[r + 3]; }
;       ps = (s0 + s1) + (s2 + s3); }
;     { auto rr = __builtin_amdgcn_permlane32_swap(__float_as_uint(ps), __float_as_uint(ps), false, false);
;       ps = __uint_as_float(rr[0]) + __uint_as_float(rr[1]); }
;     l_reg = l_reg * alpha + ps;
; __device__ __forceinline__ void block(const BlockRef& cur, const BlockRef& nxt, int skv, char* lds, Seam& S) {
;     ...
;     for (int t = 1; t + 1 < NT; t += 2) {
;         HALF_STEP(pB0, pB1, mnB, alB, pA0, pA1, alA, t, 1, 0, 0);
;         HALF_STEP(pA0, pA1, mnA, alA, pB0, pB1, alB, t + 1, 0, 1, 1);
.LBB0_399:
	s_waitcnt lgkmcnt(0)
	s_barrier
	v_cndmask_b32_e64 v188, v2, v235, s[6:7]
	v_mul_f32_e32 v2, 0xbe0293ee, v188
	v_fmamk_f32 v116, v116, 0x3e0293ee, v2
	v_fmamk_f32 v117, v117, 0x3e0293ee, v2
	v_fmamk_f32 v118, v118, 0x3e0293ee, v2
	v_fmamk_f32 v119, v119, 0x3e0293ee, v2
	v_fmamk_f32 v120, v120, 0x3e0293ee, v2
	v_fmamk_f32 v121, v121, 0x3e0293ee, v2
	v_fmamk_f32 v122, v122, 0x3e0293ee, v2
	v_fmamk_f32 v123, v123, 0x3e0293ee, v2
	v_fmamk_f32 v172, v124, 0x3e0293ee, v2
	v_fmamk_f32 v173, v125, 0x3e0293ee, v2
	v_fmamk_f32 v174, v126, 0x3e0293ee, v2
	v_fmamk_f32 v175, v127, 0x3e0293ee, v2
	s_waitcnt vmcnt(0)
	v_fmamk_f32 v176, v128, 0x3e0293ee, v2
	v_fmamk_f32 v177, v129, 0x3e0293ee, v2
	v_fmamk_f32 v178, v130, 0x3e0293ee, v2
	v_fmamk_f32 v179, v131, 0x3e0293ee, v2
	v_exp_f32_e32 v129, v116
	v_exp_f32_e32 v131, v117
	v_exp_f32_e32 v128, v118
	v_exp_f32_e32 v130, v119
	v_exp_f32_e32 v125, v120
	v_exp_f32_e32 v127, v121
	v_exp_f32_e32 v124, v122
	v_exp_f32_e32 v126, v123
	v_exp_f32_e32 v121, v172
	v_exp_f32_e32 v123, v173
	v_exp_f32_e32 v120, v174
	v_exp_f32_e32 v122, v175
	v_exp_f32_e32 v117, v176
	v_exp_f32_e32 v119, v177
	v_exp_f32_e32 v116, v178
	v_exp_f32_e32 v118, v179
	v_pk_fma_f32 v[186:187], v[100:101], s[38:39], v[2:3] op_sel_hi:[1,0,0]
	v_pk_fma_f32 v[184:185], v[102:103], s[38:39], v[2:3] op_sel_hi:[1,0,0]
	v_pk_fma_f32 v[182:183], v[104:105], s[38:39], v[2:3] op_sel_hi:[1,0,0]
	v_pk_fma_f32 v[180:181], v[106:107], s[38:39], v[2:3] op_sel_hi:[1,0,0]
	v_pk_fma_f32 v[178:179], v[108:109], s[38:39], v[2:3] op_sel_hi:[1,0,0]
	v_pk_fma_f32 v[176:177], v[110:111], s[38:39], v[2:3] op_sel_hi:[1,0,0]
	v_pk_fma_f32 v[174:175], v[112:113], s[38:39], v[2:3] op_sel_hi:[1,0,0]
	v_pk_fma_f32 v[172:173], v[114:115], s[38:39], v[2:3] op_sel_hi:[1,0,0]
	v_add_f32_e32 v2, v211, v213
	v_fmac_f32_e32 v2, v201, v232
	v_add_f32_e32 v232, v237, v238
	s_addk_i32 s74, 0x80
	s_add_i32 s73, s73, 2
	v_fmac_f32_e32 v232, v2, v233
	s_cmp_ge_u32 s73, s72
	v_add_u32_e32 v207, 0xffffff80, v207
	s_cbranch_scc1 .LBB0_401
	v_mov_b32_e32 v201, v189
	s_branch .LBB0_383
